# attention: alpha fast path out of line + per-lane partial row sums (cross-lane combine once per unit), precise vmcnt for second-half staging
# speedup vs baseline: 1.0184x; 1.0037x over previous
; #define SBAR() __builtin_amdgcn_sched_barrier(0)
; #define SLOAD(i, k0) do { sr_[i].vs0 = St::ld8(&Vh[(long)((k0) + sr) * LDK + sc]); sr_[i].vs1 = St::ld8(&Vh[(long)((k0) + 32 + sr) * LDK + sc]); \
;     sr_[i].ks0 = St::ld8(&Kh[(long)((k0) + sr) * LDK + sc]); sr_[i].ks1 = St::ld8(&Kh[(long)((k0) + 32 + sr) * LDK + sc]); } while (0)
; __device__ __forceinline__ void finishSM(f32x16& p0, f32x16& p1, float alpha, float& l_reg, bf16x8& pa0, bf16x8& pa1, bf16x8& pa2, bf16x8& pa3) {
;   for (int r = 0; r < 16; ++r) p1[r] = __builtin_amdgcn_exp2f(p1[r]);
;   float ps = 0; for (int r = 0; r < 16; ++r) ps += p0[r]; for (int r = 0; r < 16; ++r) ps += p1[r];
;   { auto rr = __builtin_amdgcn_permlane32_swap(__float_as_uint(ps), __float_as_uint(ps), false, false);
;     ps = __uint_as_float(rr[0]) + __uint_as_float(rr[1]); }
;   l_reg = l_reg * alpha + ps;
; template <typename TQ>
; __device__ __forceinline__ void attn_dense_body(const TQ* __restrict__ Qb, const bf16* __restrict__ Kh, const bf16* __restrict__ Vh,
;                                                 unsigned short* __restrict__ Ob, int seq, char* lds, const int wave_s) {
;     ...
;     SBAR(); qkt(pB0, pB1, (bf16*)((char*)K_lds + SHM_K), qr, r32, hi);
;     finishSM(pA0, pA1, alA, l_reg, pa0, pa1, pa2, pa3); SBAR();
;     SLOAD(SO, (j + SDEPTH) * KVBLK); SBAR();
;     pv_d0(o, vb0, pa0, pa1, pa2, pa3); partialSM(pB0, pB1, m_reg, mnB, alB);
.LBB0_575:
	ds_read_b128 v[64:67], v189 offset:49152
	ds_read_b128 v[68:71], v189 offset:57344
	ds_read_b128 v[210:213], v199 offset:49152
	ds_read_b128 v[214:217], v199 offset:57344
	ds_read_b128 v[240:243], v192 offset:49152
	ds_read_b128 v[244:247], v192 offset:57344
	v_add_f32_e32 v160, v175, v161
	s_waitcnt lgkmcnt(5)
	v_mfma_f32_32x32x16_bf16 v[80:95], v[64:67], v[112:115], 0
	v_add_f32_e32 v160, v162, v160
	v_add_f32_e32 v160, v206, v160
	v_add_f32_e32 v160, v174, v160
	v_add_f32_e32 v160, v209, v160
	v_add_f32_e32 v160, v163, v160
	v_add_f32_e32 v160, v173, v160
	v_add_f32_e32 v160, v169, v160
	s_waitcnt lgkmcnt(4)
	v_mfma_f32_32x32x16_bf16 v[64:79], v[68:71], v[112:115], 0
	v_add_f32_e32 v160, v171, v160
	v_add_f32_e32 v160, v170, v160
	v_add_f32_e32 v160, v172, v160
	v_exp_f32_e32 v158, v158
	v_add_f32_e32 v160, v165, v160
	v_exp_f32_e32 v159, v159
	v_add_f32_e32 v160, v167, v160
	s_waitcnt lgkmcnt(3)
	v_mfma_f32_32x32x16_bf16 v[80:95], v[210:213], v[108:111], v[80:95]
	v_exp_f32_e32 v156, v156
	v_add_f32_e32 v160, v166, v160
	v_exp_f32_e32 v157, v157
	v_add_f32_e32 v160, v168, v160
	v_exp_f32_e32 v152, v152
	v_add_f32_e32 v160, v158, v160
	v_exp_f32_e32 v153, v153
	s_waitcnt lgkmcnt(2)
	v_mfma_f32_32x32x16_bf16 v[64:79], v[214:217], v[108:111], v[64:79]
	ds_read_b128 v[210:213], v191 offset:49152
	ds_read_b128 v[214:217], v191 offset:57344
	v_add_f32_e32 v160, v159, v160
	v_exp_f32_e32 v148, v148
	v_add_f32_e32 v160, v156, v160
	v_exp_f32_e32 v149, v149
	v_add_f32_e32 v160, v157, v160
	v_exp_f32_e32 v146, v146
	s_waitcnt lgkmcnt(3)
	v_mfma_f32_32x32x16_bf16 v[80:95], v[240:243], v[120:123], v[80:95]
	v_add_f32_e32 v160, v152, v160
	v_exp_f32_e32 v147, v147
	v_add_f32_e32 v160, v153, v160
	v_exp_f32_e32 v154, v154
	v_add_f32_e32 v160, v148, v160
	v_exp_f32_e32 v155, v155
	v_add_f32_e32 v160, v149, v160
	s_waitcnt lgkmcnt(2)
	v_mfma_f32_32x32x16_bf16 v[64:79], v[244:247], v[120:123], v[64:79]
	ds_read_b128 v[240:243], v189 offset:49280
	ds_read_b128 v[244:247], v189 offset:57472
	v_exp_f32_e32 v150, v150
	v_add_f32_e32 v160, v146, v160
	v_exp_f32_e32 v151, v151
	v_add_f32_e32 v160, v147, v160
	v_exp_f32_e32 v144, v144
	v_add_f32_e32 v160, v154, v160
	s_waitcnt lgkmcnt(3)
	v_mfma_f32_32x32x16_bf16 v[80:95], v[210:213], v[124:127], v[80:95]
	v_exp_f32_e32 v145, v145
	v_add_f32_e32 v160, v155, v160
	v_add_f32_e32 v160, v150, v160
	v_add_f32_e32 v160, v151, v160
	v_add_f32_e32 v160, v144, v160
	v_add_f32_e32 v203, v145, v160
	s_waitcnt lgkmcnt(2)
	v_mfma_f32_32x32x16_bf16 v[64:79], v[214:217], v[124:127], v[64:79]
	ds_read_b128 v[210:213], v199 offset:49280
	ds_read_b128 v[214:217], v199 offset:57472
	s_waitcnt lgkmcnt(3)
	v_mfma_f32_32x32x16_bf16 v[80:95], v[240:243], v[116:119], v[80:95]
	s_waitcnt lgkmcnt(2)
	v_mfma_f32_32x32x16_bf16 v[64:79], v[244:247], v[116:119], v[64:79]
	ds_read_b128 v[240:243], v192 offset:49280
	ds_read_b128 v[244:247], v192 offset:57472
	s_waitcnt lgkmcnt(3)
	v_mfma_f32_32x32x16_bf16 v[80:95], v[210:213], v[104:107], v[80:95]
	s_waitcnt lgkmcnt(2)
	v_mfma_f32_32x32x16_bf16 v[64:79], v[214:217], v[104:107], v[64:79]
	ds_read_b128 v[210:213], v191 offset:49280
	ds_read_b128 v[214:217], v191 offset:57472
	s_waitcnt lgkmcnt(3)
	v_mfma_f32_32x32x16_bf16 v[80:95], v[240:243], v[100:103], v[80:95]
	s_waitcnt lgkmcnt(2)
	v_mfma_f32_32x32x16_bf16 v[64:79], v[244:247], v[100:103], v[64:79]
	v_cvt_pk_bf16_f32 v160, v161, v175
	v_cvt_pk_bf16_f32 v161, v162, v206
	v_cvt_pk_bf16_f32 v162, v174, v209
	v_cvt_pk_bf16_f32 v163, v163, v173
	v_cvt_pk_bf16_f32 v206, v169, v171
	v_cvt_pk_bf16_f32 v207, v170, v172
	s_waitcnt lgkmcnt(1)
	v_mfma_f32_32x32x16_bf16 v[80:95], v[210:213], v[96:99], v[80:95]
	v_cvt_pk_bf16_f32 v208, v165, v167
	v_cvt_pk_bf16_f32 v209, v166, v168
	v_cvt_pk_bf16_f32 v166, v158, v159
	v_cvt_pk_bf16_f32 v167, v156, v157
	v_cvt_pk_bf16_f32 v168, v152, v153
	s_waitcnt lgkmcnt(0)
	v_mfma_f32_32x32x16_bf16 v[64:79], v[214:217], v[96:99], v[64:79]
	v_cvt_pk_bf16_f32 v169, v148, v149
	v_cvt_pk_bf16_f32 v170, v146, v147
	v_cvt_pk_bf16_f32 v171, v154, v155
	v_cvt_pk_bf16_f32 v172, v150, v151
	v_cvt_pk_bf16_f32 v173, v144, v145
	global_load_dwordx4 v[144:147], v176, s[52:53]
	global_load_dwordx4 v[148:151], v176, s[52:53] offset:-512
	s_add_u32 s52, s52, 0x18000
	s_addc_u32 s53, s53, 0
	global_load_dwordx4 v[156:159], v176, s[52:53]
	global_load_dwordx4 v[152:155], v176, s[52:53] offset:-512
	s_add_u32 s52, s52, 0x18000
	s_addc_u32 s53, s53, 0
	ds_read_b64_tr_b16 v[210:211], v184 offset:0
	ds_read_b64_tr_b16 v[212:213], v184 offset:0x800
	ds_read_b64_tr_b16 v[214:215], v184 offset:0x1000
	ds_read_b64_tr_b16 v[216:217], v184 offset:0x1800
	ds_read_b64_tr_b16 v[224:225], v184 offset:0x2000
	ds_read_b64_tr_b16 v[226:227], v184 offset:0x2800
	ds_read_b64_tr_b16 v[228:229], v184 offset:0x3000
	ds_read_b64_tr_b16 v[230:231], v184 offset:0x3800
	s_waitcnt lgkmcnt(0)
	v_mfma_f32_32x32x16_bf16 v[0:15], v[160:163], v[210:213], v[0:15]
	ds_read_b64_tr_b16 v[210:211], v184 offset:0x200
	ds_read_b64_tr_b16 v[212:213], v184 offset:0xa00
	v_mfma_f32_32x32x16_bf16 v[0:15], v[206:209], v[214:217], v[0:15]
	ds_read_b64_tr_b16 v[214:215], v184 offset:0x1200
	ds_read_b64_tr_b16 v[216:217], v184 offset:0x1a00
	v_mfma_f32_32x32x16_bf16 v[0:15], v[166:169], v[224:227], v[0:15]
	ds_read_b64_tr_b16 v[224:225], v184 offset:0x2200
	ds_read_b64_tr_b16 v[226:227], v184 offset:0x2a00
	v_mfma_f32_32x32x16_bf16 v[0:15], v[170:173], v[228:231], v[0:15]
	ds_read_b64_tr_b16 v[228:229], v184 offset:0x3200
	ds_read_b64_tr_b16 v[230:231], v184 offset:0x3a00
	s_waitcnt lgkmcnt(0)
; #define SWAIT() do { if constexpr (SDEPTH == 2) asm volatile("s_waitcnt vmcnt(4)" ::: "memory"); else asm volatile("s_waitcnt vmcnt(0)" ::: "memory"); } while (0)
; #define RESC(a) do { if (__any((a) < 1.f)) { if (hi == 0) al_l[r32] = (a); asm volatile("s_waitcnt lgkmcnt(0)" ::: "memory"); \
;     for (int d = 0; d < 4; ++d) for (int r = 0; r < 16; ++r) o[d][r] *= al_l[crow(r, hi)]; } } while (0)
; __device__ __forceinline__ void partialSM(f32x16& p0, f32x16& p1, float& m_reg, float& mn, float& alpha) {
;     ...
;   if (__builtin_expect(__all(pmax - m_reg <= THR / SCALE), 1)) { mn = m_reg; alpha = 1.f; }
;   else { mn = fmaxf(m_reg, pmax); alpha = __builtin_amdgcn_exp2f((m_reg - mn) * C); m_reg = mn; }
;   float mnC = -mn * C;
; template <typename TQ>
; __device__ __forceinline__ void attn_dense_body(const TQ* __restrict__ Qb, const bf16* __restrict__ Kh, const bf16* __restrict__ Vh,
;                                                 unsigned short* __restrict__ Ob, int seq, char* lds, const int wave_s) {
;     ...
;     pv_d0(o, vb0, pa0, pa1, pa2, pa3); partialSM(pB0, pB1, m_reg, mnB, alB);
;     __syncthreads(); SWAIT(); SWRITE(0, SE);
;     RESC(alB); __syncthreads();
	v_mfma_f32_32x32x16_bf16 v[48:63], v[160:163], v[210:213], v[48:63]
	ds_read_b64_tr_b16 v[210:211], v184 offset:0x400
	ds_read_b64_tr_b16 v[212:213], v184 offset:0xc00
	v_mfma_f32_32x32x16_bf16 v[48:63], v[206:209], v[214:217], v[48:63]
	ds_read_b64_tr_b16 v[214:215], v184 offset:0x1400
	ds_read_b64_tr_b16 v[216:217], v184 offset:0x1c00
	v_mfma_f32_32x32x16_bf16 v[48:63], v[166:169], v[224:227], v[48:63]
	ds_read_b64_tr_b16 v[224:225], v184 offset:0x2400
	ds_read_b64_tr_b16 v[226:227], v184 offset:0x2c00
	v_mfma_f32_32x32x16_bf16 v[48:63], v[170:173], v[228:231], v[48:63]
	ds_read_b64_tr_b16 v[228:229], v184 offset:0x3400
	ds_read_b64_tr_b16 v[230:231], v184 offset:0x3c00
	s_waitcnt lgkmcnt(0)
	v_mfma_f32_32x32x16_bf16 v[32:47], v[160:163], v[210:213], v[32:47]
	ds_read_b64_tr_b16 v[210:211], v184 offset:0x600
	ds_read_b64_tr_b16 v[212:213], v184 offset:0xe00
	v_mfma_f32_32x32x16_bf16 v[32:47], v[206:209], v[214:217], v[32:47]
	ds_read_b64_tr_b16 v[214:215], v184 offset:0x1600
	ds_read_b64_tr_b16 v[216:217], v184 offset:0x1e00
	v_mfma_f32_32x32x16_bf16 v[32:47], v[166:169], v[224:227], v[32:47]
	ds_read_b64_tr_b16 v[224:225], v184 offset:0x2600
	ds_read_b64_tr_b16 v[226:227], v184 offset:0x2e00
	v_mfma_f32_32x32x16_bf16 v[32:47], v[170:173], v[228:231], v[32:47]
	ds_read_b64_tr_b16 v[228:229], v184 offset:0x3600
	ds_read_b64_tr_b16 v[230:231], v184 offset:0x3e00
	s_waitcnt lgkmcnt(0)
	v_mfma_f32_32x32x16_bf16 v[16:31], v[160:163], v[210:213], v[16:31]
	v_max_f32_e32 v160, v80, v81
	v_max3_f32 v160, v160, v82, v83
	v_max3_f32 v160, v160, v84, v85
	v_max3_f32 v160, v160, v86, v87
	v_max3_f32 v160, v160, v88, v89
	v_max3_f32 v160, v160, v90, v91
	v_max3_f32 v160, v160, v92, v93
	v_mfma_f32_32x32x16_bf16 v[16:31], v[206:209], v[214:217], v[16:31]
	v_max3_f32 v160, v160, v94, v95
	v_max3_f32 v160, v160, v64, v65
	v_max3_f32 v160, v160, v66, v67
	v_max3_f32 v160, v160, v68, v69
	v_max3_f32 v160, v160, v70, v71
	v_max3_f32 v160, v160, v72, v73
	v_max3_f32 v160, v160, v74, v75
	v_max3_f32 v160, v160, v76, v77
	v_mfma_f32_32x32x16_bf16 v[16:31], v[166:169], v[224:227], v[16:31]
	v_max3_f32 v160, v160, v78, v79
	v_mov_b32_e32 v161, v160
	s_nop 1
	v_permlane32_swap_b32_e32 v160, v161
	v_max_f32_e32 v160, v160, v161
	v_sub_f32_e32 v161, v160, v164
	v_cmp_ge_f32_e32 vcc, s9, v161
	v_mfma_f32_32x32x16_bf16 v[16:31], v[170:173], v[228:231], v[16:31]
	s_cmp_eq_u64 vcc, exec
	s_cbranch_scc0 .Lattn_slow_a
	v_mov_b32_e32 v205, 1.0
	v_mov_b32_e32 v206, v164
	s_waitcnt vmcnt(4)
	ds_write_b128 v187, v[128:131]
	ds_write_b128 v187, v[136:139] offset:8192
	ds_write_b128 v185, v[132:135] offset:32768
	ds_write_b128 v185, v[140:143] offset:40960
.LBB0_579:
	v_xor_b32_e32 v189, 0x18000, v189
	v_xor_b32_e32 v199, 0x18000, v199
	v_xor_b32_e32 v192, 0x18000, v192
	v_xor_b32_e32 v191, 0x18000, v191
	v_mul_f32_e32 v207, 0xbe0293ee, v206
	v_fmamk_f32 v80, v80, 0x3e0293ee, v207
	v_fmamk_f32 v81, v81, 0x3e0293ee, v207
	v_fmamk_f32 v82, v82, 0x3e0293ee, v207
	v_fmamk_f32 v83, v83, 0x3e0293ee, v207
	v_fmamk_f32 v84, v84, 0x3e0293ee, v207
	v_fmamk_f32 v85, v85, 0x3e0293ee, v207
	v_fmamk_f32 v86, v86, 0x3e0293ee, v207
	v_fmamk_f32 v87, v87, 0x3e0293ee, v207
	v_fmamk_f32 v88, v88, 0x3e0293ee, v207
	v_fmamk_f32 v89, v89, 0x3e0293ee, v207
	v_fmamk_f32 v90, v90, 0x3e0293ee, v207
	v_fmamk_f32 v91, v91, 0x3e0293ee, v207
	v_fmamk_f32 v92, v92, 0x3e0293ee, v207
	v_fmamk_f32 v93, v93, 0x3e0293ee, v207
	v_fmamk_f32 v94, v94, 0x3e0293ee, v207
	v_fmamk_f32 v95, v95, 0x3e0293ee, v207
	v_exp_f32_e32 v160, v80
	v_exp_f32_e32 v175, v81
	v_exp_f32_e32 v161, v82
	v_exp_f32_e32 v174, v83
	v_exp_f32_e32 v162, v84
	v_exp_f32_e32 v173, v85
	v_exp_f32_e32 v163, v86
	v_exp_f32_e32 v172, v87
	v_exp_f32_e32 v164, v88
	v_exp_f32_e32 v171, v89
	v_exp_f32_e32 v165, v90
	v_exp_f32_e32 v170, v91
	v_exp_f32_e32 v166, v92
	v_exp_f32_e32 v169, v93
	v_exp_f32_e32 v167, v94
	v_exp_f32_e32 v168, v95
	v_fmamk_f32 v216, v64, 0x3e0293ee, v207
	v_fmamk_f32 v217, v65, 0x3e0293ee, v207
	v_fmamk_f32 v218, v66, 0x3e0293ee, v207
	v_fmamk_f32 v219, v67, 0x3e0293ee, v207
	v_fmamk_f32 v224, v68, 0x3e0293ee, v207
	v_fmamk_f32 v209, v69, 0x3e0293ee, v207
	v_fmamk_f32 v210, v70, 0x3e0293ee, v207
	v_fmamk_f32 v211, v71, 0x3e0293ee, v207
	v_fmamk_f32 v212, v72, 0x3e0293ee, v207
	v_fmamk_f32 v213, v73, 0x3e0293ee, v207
	v_fmamk_f32 v214, v74, 0x3e0293ee, v207
	v_fmamk_f32 v215, v75, 0x3e0293ee, v207
	v_fmamk_f32 v208, v76, 0x3e0293ee, v207
	v_fmamk_f32 v225, v77, 0x3e0293ee, v207
	v_fmamk_f32 v226, v78, 0x3e0293ee, v207
	v_fmac_f32_e32 v207, 0x3e0293ee, v79
	s_waitcnt lgkmcnt(0)
	s_barrier
; #define SBAR() __builtin_amdgcn_sched_barrier(0)
; #define SLOAD(i, k0) do { sr_[i].vs0 = St::ld8(&Vh[(long)((k0) + sr) * LDK + sc]); sr_[i].vs1 = St::ld8(&Vh[(long)((k0) + 32 + sr) * LDK + sc]); \
;     sr_[i].ks0 = St::ld8(&Kh[(long)((k0) + sr) * LDK + sc]); sr_[i].ks1 = St::ld8(&Kh[(long)((k0) + 32 + sr) * LDK + sc]); } while (0)
; __device__ __forceinline__ void finishSM(f32x16& p0, f32x16& p1, float alpha, float& l_reg, bf16x8& pa0, bf16x8& pa1, bf16x8& pa2, bf16x8& pa3) {
;   for (int r = 0; r < 16; ++r) p1[r] = __builtin_amdgcn_exp2f(p1[r]);
;   float ps = 0; for (int r = 0; r < 16; ++r) ps += p0[r]; for (int r = 0; r < 16; ++r) ps += p1[r];
;   { auto rr = __builtin_amdgcn_permlane32_swap(__float_as_uint(ps), __float_as_uint(ps), false, false);
;     ps = __uint_as_float(rr[0]) + __uint_as_float(rr[1]); }
;   l_reg = l_reg * alpha + ps;
; template <typename TQ>
; __device__ __forceinline__ void attn_dense_body(const TQ* __restrict__ Qb, const bf16* __restrict__ Kh, const bf16* __restrict__ Vh,
;                                                 unsigned short* __restrict__ Ob, int seq, char* lds, const int wave_s) {
;     ...
;     SBAR(); qkt(pA0, pA1, K_lds, qr, r32, hi);
;     finishSM(pB0, pB1, alB, l_reg, pa0, pa1, pa2, pa3); SBAR();
;     if (SDEPTH == 1 || j + 3 < NT) SLOAD(SE, (j + 1 + SDEPTH) * KVBLK); SBAR();
	ds_read_b128 v[64:67], v189 offset:32768
	ds_read_b128 v[68:71], v189 offset:40960
	ds_read_b128 v[228:231], v199 offset:32768
	ds_read_b128 v[232:235], v199 offset:40960
	ds_read_b128 v[240:243], v192 offset:32768
	ds_read_b128 v[244:247], v192 offset:40960
	v_exp_f32_e32 v221, v207
	s_waitcnt lgkmcnt(5)
	v_mfma_f32_32x32x16_bf16 v[80:95], v[64:67], v[112:115], 0
	v_add_f32_e32 v207, v175, v160
	v_add_f32_e32 v207, v161, v207
	v_add_f32_e32 v207, v174, v207
	v_add_f32_e32 v207, v162, v207
	v_add_f32_e32 v207, v173, v207
	v_add_f32_e32 v207, v163, v207
	v_add_f32_e32 v207, v172, v207
	s_waitcnt lgkmcnt(4)
	v_mfma_f32_32x32x16_bf16 v[64:79], v[68:71], v[112:115], 0
	v_add_f32_e32 v207, v164, v207
	v_add_f32_e32 v207, v171, v207
	v_add_f32_e32 v207, v165, v207
	v_add_f32_e32 v207, v170, v207
	v_exp_f32_e32 v194, v216
	v_add_f32_e32 v207, v166, v207
	v_exp_f32_e32 v195, v217
	s_waitcnt lgkmcnt(3)
	v_mfma_f32_32x32x16_bf16 v[80:95], v[228:231], v[108:111], v[80:95]
	v_add_f32_e32 v207, v169, v207
	v_exp_f32_e32 v196, v218
	v_add_f32_e32 v207, v167, v207
	v_exp_f32_e32 v197, v219
	v_add_f32_e32 v207, v168, v207
	v_exp_f32_e32 v216, v224
	v_add_f32_e32 v207, v194, v207
	s_waitcnt lgkmcnt(2)
	v_mfma_f32_32x32x16_bf16 v[64:79], v[232:235], v[108:111], v[64:79]
	ds_read_b128 v[228:231], v191 offset:32768
	ds_read_b128 v[232:235], v191 offset:40960
	v_exp_f32_e32 v209, v209
	v_add_f32_e32 v207, v195, v207
	v_exp_f32_e32 v210, v210
	v_add_f32_e32 v207, v196, v207
	v_exp_f32_e32 v211, v211
	v_add_f32_e32 v207, v197, v207
	s_waitcnt lgkmcnt(3)
	v_mfma_f32_32x32x16_bf16 v[80:95], v[240:243], v[120:123], v[80:95]
	v_exp_f32_e32 v212, v212
	v_add_f32_e32 v207, v216, v207
	v_exp_f32_e32 v213, v213
	v_add_f32_e32 v207, v209, v207
	v_exp_f32_e32 v214, v214
	v_add_f32_e32 v207, v210, v207
	v_exp_f32_e32 v215, v215
	s_waitcnt lgkmcnt(2)
	v_mfma_f32_32x32x16_bf16 v[64:79], v[244:247], v[120:123], v[64:79]
	ds_read_b128 v[240:243], v189 offset:32896
	ds_read_b128 v[244:247], v189 offset:41088
	v_add_f32_e32 v207, v211, v207
	v_exp_f32_e32 v217, v208
	v_add_f32_e32 v207, v212, v207
	v_exp_f32_e32 v218, v225
	v_add_f32_e32 v207, v213, v207
	v_exp_f32_e32 v219, v226
	s_waitcnt lgkmcnt(3)
	v_mfma_f32_32x32x16_bf16 v[80:95], v[228:231], v[124:127], v[80:95]
	v_add_f32_e32 v207, v214, v207
	v_add_f32_e32 v207, v215, v207
	v_add_f32_e32 v207, v217, v207
	v_add_f32_e32 v207, v218, v207
	v_add_f32_e32 v207, v219, v207
	v_add_f32_e32 v207, v221, v207
	s_waitcnt lgkmcnt(2)
	v_mfma_f32_32x32x16_bf16 v[64:79], v[232:235], v[124:127], v[64:79]
	ds_read_b128 v[228:231], v199 offset:32896
	ds_read_b128 v[232:235], v199 offset:41088
	s_waitcnt lgkmcnt(3)
	v_mfma_f32_32x32x16_bf16 v[80:95], v[240:243], v[116:119], v[80:95]
	s_waitcnt lgkmcnt(2)
	v_mfma_f32_32x32x16_bf16 v[64:79], v[244:247], v[116:119], v[64:79]
	ds_read_b128 v[240:243], v192 offset:32896
	ds_read_b128 v[244:247], v192 offset:41088
	s_waitcnt lgkmcnt(3)
	v_mfma_f32_32x32x16_bf16 v[80:95], v[228:231], v[104:107], v[80:95]
	s_waitcnt lgkmcnt(2)
	v_mfma_f32_32x32x16_bf16 v[64:79], v[232:235], v[104:107], v[64:79]
	ds_read_b128 v[228:231], v191 offset:32896
	ds_read_b128 v[232:235], v191 offset:41088
	s_waitcnt lgkmcnt(3)
	v_mfma_f32_32x32x16_bf16 v[80:95], v[240:243], v[100:103], v[80:95]
	s_waitcnt lgkmcnt(2)
	v_mfma_f32_32x32x16_bf16 v[64:79], v[244:247], v[100:103], v[64:79]
	v_cvt_pk_bf16_f32 v160, v160, v175
	v_cvt_pk_bf16_f32 v161, v161, v174
	v_cvt_pk_bf16_f32 v162, v162, v173
	v_cvt_pk_bf16_f32 v163, v163, v172
	v_cvt_pk_bf16_f32 v164, v164, v171
	v_cvt_pk_bf16_f32 v165, v165, v170
	s_waitcnt lgkmcnt(1)
	v_mfma_f32_32x32x16_bf16 v[80:95], v[228:231], v[96:99], v[80:95]
	v_cvt_pk_bf16_f32 v166, v166, v169
	v_cvt_pk_bf16_f32 v167, v167, v168
	v_cvt_pk_bf16_f32 v168, v194, v195
	v_cvt_pk_bf16_f32 v169, v196, v197
	v_cvt_pk_bf16_f32 v170, v216, v209
	v_cvt_pk_bf16_f32 v171, v210, v211
	v_cvt_pk_bf16_f32 v172, v212, v213
	s_waitcnt lgkmcnt(0)
	v_mfma_f32_32x32x16_bf16 v[64:79], v[232:235], v[96:99], v[64:79]
	v_cvt_pk_bf16_f32 v173, v214, v215
	v_cvt_pk_bf16_f32 v174, v217, v218
	v_cvt_pk_bf16_f32 v175, v219, v221
	s_add_i32 s50, s50, 2
	s_cmp_ge_u32 s50, s49
	s_cselect_b64 s[44:45], -1, 0
	s_and_b64 vcc, exec, s[44:45]
	s_cbranch_vccnz .Lattn_skip_loads
	global_load_dwordx4 v[128:131], v176, s[52:53]
	global_load_dwordx4 v[132:135], v176, s[52:53] offset:-512
	s_add_u32 s52, s52, 0x18000
	s_addc_u32 s53, s53, 0
	global_load_dwordx4 v[136:139], v176, s[52:53]
	global_load_dwordx4 v[140:143], v176, s[52:53] offset:-512
	s_add_u32 s52, s52, 0x18000
	s_addc_u32 s53, s53, 0
; #define SWAIT() do { if constexpr (SDEPTH == 2) asm volatile("s_waitcnt vmcnt(4)" ::: "memory"); else asm volatile("s_waitcnt vmcnt(0)" ::: "memory"); } while (0)
; #define RESC(a) do { if (__any((a) < 1.f)) { if (hi == 0) al_l[r32] = (a); asm volatile("s_waitcnt lgkmcnt(0)" ::: "memory"); \
;     for (int d = 0; d < 4; ++d) for (int r = 0; r < 16; ++r) o[d][r] *= al_l[crow(r, hi)]; } } while (0)
; __device__ __forceinline__ void partialSM(f32x16& p0, f32x16& p1, float& m_reg, float& mn, float& alpha) {
;     ...
;   if (__builtin_expect(__all(pmax - m_reg <= THR / SCALE), 1)) { mn = m_reg; alpha = 1.f; }
;   else { mn = fmaxf(m_reg, pmax); alpha = __builtin_amdgcn_exp2f((m_reg - mn) * C); m_reg = mn; }
;   float mnC = -mn * C;
;   for (int r = 0; r < 16; ++r) p0[r] = fmaf(p0[r], C, mnC); for (int r = 0; r < 16; ++r) p1[r] = fmaf(p1[r], C, mnC);
;   for (int r = 0; r < 16; ++r) p0[r] = __builtin_amdgcn_exp2f(p0[r]);
; template <typename TQ>
; __device__ __forceinline__ void attn_dense_body(const TQ* __restrict__ Qb, const bf16* __restrict__ Kh, const bf16* __restrict__ Vh,
;                                                 unsigned short* __restrict__ Ob, int seq, char* lds, const int wave_s) {
;     ...
;     pv_d0(o, vb0 + (int)SHM_V, pa0, pa1, pa2, pa3); partialSM(pA0, pA1, m_reg, mnA, alA);
;     __syncthreads(); SWAIT(); SWRITE(1, SO);
;     RESC(alA); __syncthreads();
.LBB0_581:
	ds_read_b64_tr_b16 v[210:211], v184 offset:16384
	ds_read_b64_tr_b16 v[212:213], v184 offset:18432
	ds_read_b64_tr_b16 v[214:215], v184 offset:20480
	ds_read_b64_tr_b16 v[216:217], v184 offset:22528
	ds_read_b64_tr_b16 v[224:225], v184 offset:24576
	ds_read_b64_tr_b16 v[226:227], v184 offset:26624
	ds_read_b64_tr_b16 v[228:229], v184 offset:28672
	ds_read_b64_tr_b16 v[230:231], v184 offset:30720
	s_waitcnt lgkmcnt(0)
	v_mfma_f32_32x32x16_bf16 v[0:15], v[160:163], v[210:213], v[0:15]
	ds_read_b64_tr_b16 v[210:211], v184 offset:16896
	ds_read_b64_tr_b16 v[212:213], v184 offset:18944
	v_mfma_f32_32x32x16_bf16 v[0:15], v[164:167], v[214:217], v[0:15]
	ds_read_b64_tr_b16 v[214:215], v184 offset:20992
	ds_read_b64_tr_b16 v[216:217], v184 offset:23040
	v_mfma_f32_32x32x16_bf16 v[0:15], v[168:171], v[224:227], v[0:15]
	ds_read_b64_tr_b16 v[224:225], v184 offset:25088
	ds_read_b64_tr_b16 v[226:227], v184 offset:27136
	v_mfma_f32_32x32x16_bf16 v[0:15], v[172:175], v[228:231], v[0:15]
	ds_read_b64_tr_b16 v[228:229], v184 offset:29184
	ds_read_b64_tr_b16 v[230:231], v184 offset:31232
	s_waitcnt lgkmcnt(0)
	v_mfma_f32_32x32x16_bf16 v[48:63], v[160:163], v[210:213], v[48:63]
	ds_read_b64_tr_b16 v[210:211], v184 offset:17408
	ds_read_b64_tr_b16 v[212:213], v184 offset:19456
	v_mfma_f32_32x32x16_bf16 v[48:63], v[164:167], v[214:217], v[48:63]
	ds_read_b64_tr_b16 v[214:215], v184 offset:21504
	ds_read_b64_tr_b16 v[216:217], v184 offset:23552
	v_mfma_f32_32x32x16_bf16 v[48:63], v[168:171], v[224:227], v[48:63]
	ds_read_b64_tr_b16 v[224:225], v184 offset:25600
	ds_read_b64_tr_b16 v[226:227], v184 offset:27648
	v_mfma_f32_32x32x16_bf16 v[48:63], v[172:175], v[228:231], v[48:63]
	ds_read_b64_tr_b16 v[228:229], v184 offset:29696
	ds_read_b64_tr_b16 v[230:231], v184 offset:31744
	s_waitcnt lgkmcnt(0)
	v_mfma_f32_32x32x16_bf16 v[32:47], v[160:163], v[210:213], v[32:47]
	ds_read_b64_tr_b16 v[210:211], v184 offset:17920
	ds_read_b64_tr_b16 v[212:213], v184 offset:19968
	v_mfma_f32_32x32x16_bf16 v[32:47], v[164:167], v[214:217], v[32:47]
	ds_read_b64_tr_b16 v[214:215], v184 offset:22016
	ds_read_b64_tr_b16 v[216:217], v184 offset:24064
	v_mfma_f32_32x32x16_bf16 v[32:47], v[168:171], v[224:227], v[32:47]
	ds_read_b64_tr_b16 v[224:225], v184 offset:26112
	ds_read_b64_tr_b16 v[226:227], v184 offset:28160
	v_mfma_f32_32x32x16_bf16 v[32:47], v[172:175], v[228:231], v[32:47]
	ds_read_b64_tr_b16 v[228:229], v184 offset:30208
	ds_read_b64_tr_b16 v[230:231], v184 offset:32256
	s_waitcnt lgkmcnt(0)
	v_mfma_f32_32x32x16_bf16 v[16:31], v[160:163], v[210:213], v[16:31]
	v_max_f32_e32 v160, v80, v81
	v_max3_f32 v160, v160, v82, v83
	v_max3_f32 v160, v160, v84, v85
	v_max3_f32 v160, v160, v86, v87
	v_max3_f32 v160, v160, v88, v89
	v_max3_f32 v160, v160, v90, v91
	v_max3_f32 v160, v160, v92, v93
	v_mfma_f32_32x32x16_bf16 v[16:31], v[164:167], v[214:217], v[16:31]
	v_max3_f32 v160, v160, v94, v95
	v_max3_f32 v160, v160, v64, v65
	v_max3_f32 v160, v160, v66, v67
	v_max3_f32 v160, v160, v68, v69
	v_max3_f32 v160, v160, v70, v71
	v_max3_f32 v160, v160, v72, v73
	v_max3_f32 v160, v160, v74, v75
	v_max3_f32 v160, v160, v76, v77
	v_mfma_f32_32x32x16_bf16 v[16:31], v[168:171], v[224:227], v[16:31]
	v_max3_f32 v160, v160, v78, v79
	v_mov_b32_e32 v161, v160
	s_nop 1
	v_permlane32_swap_b32_e32 v160, v161
	v_max_f32_e32 v160, v160, v161
	v_sub_f32_e32 v161, v160, v206
	v_cmp_ge_f32_e32 vcc, s9, v161
	v_mfma_f32_32x32x16_bf16 v[16:31], v[172:175], v[228:231], v[16:31]
	s_cmp_eq_u64 vcc, exec
	s_cbranch_scc0 .Lattn_slow_b
	v_mov_b32_e32 v164, v206
	v_mov_b32_e32 v160, 1.0
	s_waitcnt vmcnt(4)
	ds_write_b128 v187, v[144:147] offset:16384
	ds_write_b128 v187, v[156:159] offset:24576
	ds_write_b128 v185, v[148:151] offset:49152
	ds_write_b128 v185, v[152:155] offset:57344
.LBB0_585:
	v_xor_b32_e32 v184, 0x8000, v184
	v_xor_b32_e32 v187, 0x8000, v187
	v_xor_b32_e32 v185, 0x18000, v185
	v_mul_f32_e32 v144, 0xbe0293ee, v164
	v_mov_b32_e32 v145, v144
	v_fmamk_f32 v80, v80, 0x3e0293ee, v144
	v_fmamk_f32 v81, v81, 0x3e0293ee, v144
	v_fmamk_f32 v82, v82, 0x3e0293ee, v144
	v_fmamk_f32 v83, v83, 0x3e0293ee, v144
	v_fmamk_f32 v84, v84, 0x3e0293ee, v144
	v_fmamk_f32 v85, v85, 0x3e0293ee, v144
	v_fmamk_f32 v86, v86, 0x3e0293ee, v144
	v_fmamk_f32 v87, v87, 0x3e0293ee, v144
	v_fmamk_f32 v88, v88, 0x3e0293ee, v144
	v_fmamk_f32 v89, v89, 0x3e0293ee, v144
	v_fmamk_f32 v90, v90, 0x3e0293ee, v144
	v_fmamk_f32 v91, v91, 0x3e0293ee, v144
	v_fmamk_f32 v92, v92, 0x3e0293ee, v144
	v_fmamk_f32 v93, v93, 0x3e0293ee, v144
	v_fmamk_f32 v94, v94, 0x3e0293ee, v144
	v_fmac_f32_e32 v145, 0x3e0293ee, v95
	v_exp_f32_e32 v161, v80
	v_exp_f32_e32 v175, v81
	v_exp_f32_e32 v162, v82
	v_exp_f32_e32 v206, v83
	v_exp_f32_e32 v174, v84
	v_exp_f32_e32 v209, v85
	v_exp_f32_e32 v163, v86
	v_exp_f32_e32 v173, v87
	v_exp_f32_e32 v169, v88
	v_exp_f32_e32 v171, v89
	v_exp_f32_e32 v170, v90
	v_exp_f32_e32 v172, v91
	v_exp_f32_e32 v165, v92
	v_exp_f32_e32 v167, v93
	v_exp_f32_e32 v166, v94
	v_exp_f32_e32 v168, v145
	v_pk_fma_f32 v[158:159], v[64:65], s[30:31], v[144:145] op_sel_hi:[1,0,0]
	v_fma_f32 v64, v202, v182, v203
	v_pk_fma_f32 v[156:157], v[66:67], s[30:31], v[144:145] op_sel_hi:[1,0,0]
	v_pk_fma_f32 v[152:153], v[68:69], s[30:31], v[144:145] op_sel_hi:[1,0,0]
	v_pk_fma_f32 v[148:149], v[70:71], s[30:31], v[144:145] op_sel_hi:[1,0,0]
	v_pk_fma_f32 v[146:147], v[72:73], s[30:31], v[144:145] op_sel_hi:[1,0,0]
	v_pk_fma_f32 v[154:155], v[74:75], s[30:31], v[144:145] op_sel_hi:[1,0,0]
	v_pk_fma_f32 v[150:151], v[76:77], s[30:31], v[144:145] op_sel_hi:[1,0,0]
	v_pk_fma_f32 v[144:145], v[78:79], s[30:31], v[144:145] op_sel_hi:[1,0,0]
	v_fma_f32 v182, v64, v205, v207
	s_and_b64 vcc, exec, s[44:45]
	s_waitcnt lgkmcnt(0)
	s_barrier
	s_cbranch_vccnz .LBB0_587
	v_mov_b32_e32 v202, v160
	s_branch .LBB0_575
; __device__ __forceinline__ void partialSM(f32x16& p0, f32x16& p1, float& m_reg, float& mn, float& alpha) {
;     ...
;   if (__builtin_expect(__all(pmax - m_reg <= THR / SCALE), 1)) { mn = m_reg; alpha = 1.f; }
;   else { mn = fmaxf(m_reg, pmax); alpha = __builtin_amdgcn_exp2f((m_reg - mn) * C); m_reg = mn; }
.Lattn_slow_a:
	v_max_f32_e32 v160, v164, v160
	v_sub_f32_e32 v161, v164, v160
	v_mul_f32_e32 v161, 0x3e0293ee, v161
	v_exp_f32_e32 v161, v161
	s_waitcnt vmcnt(4)
	s_nop 0
	v_mov_b32_e32 v205, v161
	v_cmp_gt_f32_e32 vcc, 1.0, v205
	ds_write_b128 v187, v[128:131]
	ds_write_b128 v187, v[136:139] offset:8192
	ds_write_b128 v185, v[132:135] offset:32768
	ds_write_b128 v185, v[140:143] offset:40960
	s_cbranch_vccz .Lattn_slow_a_end
	s_and_saveexec_b64 s[44:45], s[38:39]
	ds_write_b32 v181, v205 offset:128
	s_or_b64 exec, exec, s[44:45]
	s_waitcnt lgkmcnt(0)
	v_add_u32_e32 v161, s1, v180
	ds_read_b128 v[166:169], v161 offset:224
	ds_read_b128 v[170:173], v161 offset:192
	ds_read_b128 v[206:209], v161 offset:160
	ds_read_b128 v[210:213], v161 offset:128
	s_waitcnt lgkmcnt(3)
	v_pk_mul_f32 v[12:13], v[12:13], v[166:167]
	s_waitcnt lgkmcnt(2)
	v_pk_mul_f32 v[8:9], v[8:9], v[170:171]
	s_waitcnt lgkmcnt(1)
	v_pk_mul_f32 v[4:5], v[4:5], v[206:207]
	v_pk_mul_f32 v[14:15], v[14:15], v[168:169]
	v_pk_mul_f32 v[10:11], v[10:11], v[172:173]
	v_pk_mul_f32 v[6:7], v[6:7], v[208:209]
	s_waitcnt lgkmcnt(0)
	v_pk_mul_f32 v[2:3], v[2:3], v[212:213]
	v_pk_mul_f32 v[0:1], v[0:1], v[210:211]
	v_pk_mul_f32 v[60:61], v[60:61], v[166:167]
	v_pk_mul_f32 v[56:57], v[56:57], v[170:171]
	v_pk_mul_f32 v[52:53], v[52:53], v[206:207]
	v_pk_mul_f32 v[62:63], v[62:63], v[168:169]
	v_pk_mul_f32 v[58:59], v[58:59], v[172:173]
	v_pk_mul_f32 v[54:55], v[54:55], v[208:209]
	v_pk_mul_f32 v[50:51], v[50:51], v[212:213]
	v_pk_mul_f32 v[48:49], v[48:49], v[210:211]
	v_pk_mul_f32 v[44:45], v[44:45], v[166:167]
	v_pk_mul_f32 v[40:41], v[40:41], v[170:171]
	v_pk_mul_f32 v[36:37], v[36:37], v[206:207]
	v_pk_mul_f32 v[46:47], v[46:47], v[168:169]
	v_pk_mul_f32 v[42:43], v[42:43], v[172:173]
	v_pk_mul_f32 v[38:39], v[38:39], v[208:209]
	v_pk_mul_f32 v[34:35], v[34:35], v[212:213]
	v_pk_mul_f32 v[32:33], v[32:33], v[210:211]
	v_pk_mul_f32 v[28:29], v[28:29], v[166:167]
	v_pk_mul_f32 v[24:25], v[24:25], v[170:171]
	v_pk_mul_f32 v[20:21], v[20:21], v[206:207]
	v_pk_mul_f32 v[30:31], v[30:31], v[168:169]
	v_pk_mul_f32 v[26:27], v[26:27], v[172:173]
	v_pk_mul_f32 v[22:23], v[22:23], v[208:209]
	v_pk_mul_f32 v[18:19], v[18:19], v[212:213]
	v_pk_mul_f32 v[16:17], v[16:17], v[210:211]
.Lattn_slow_a_end:
	v_mov_b32_e32 v206, v160
	s_branch .LBB0_579
.Lattn_slow_b:
	v_max_f32_e32 v161, v206, v160
	v_sub_f32_e32 v160, v206, v161
	v_mul_f32_e32 v160, 0x3e0293ee, v160
	v_exp_f32_e32 v160, v160
	s_waitcnt vmcnt(4)
	s_nop 0
	v_cmp_gt_f32_e32 vcc, 1.0, v160
	ds_write_b128 v187, v[144:147] offset:16384
	ds_write_b128 v187, v[156:159] offset:24576
	ds_write_b128 v185, v[148:151] offset:49152
	ds_write_b128 v185, v[152:155] offset:57344
	s_cbranch_vccz .Lattn_slow_b_end
	s_and_saveexec_b64 s[46:47], s[38:39]
	ds_write_b32 v181, v160 offset:128
	s_or_b64 exec, exec, s[46:47]
	s_waitcnt lgkmcnt(0)
	v_add_u32_e32 v156, s1, v180
	ds_read_b128 v[144:147], v156 offset:224
	ds_read_b128 v[148:151], v156 offset:192
	ds_read_b128 v[152:155], v156 offset:160
	ds_read_b128 v[156:159], v156 offset:128
	s_waitcnt lgkmcnt(3)
	v_pk_mul_f32 v[12:13], v[12:13], v[144:145]
	s_waitcnt lgkmcnt(2)
	v_pk_mul_f32 v[8:9], v[8:9], v[148:149]
	s_waitcnt lgkmcnt(1)
	v_pk_mul_f32 v[4:5], v[4:5], v[152:153]
	v_pk_mul_f32 v[14:15], v[14:15], v[146:147]
	v_pk_mul_f32 v[10:11], v[10:11], v[150:151]
	v_pk_mul_f32 v[6:7], v[6:7], v[154:155]
	s_waitcnt lgkmcnt(0)
	v_pk_mul_f32 v[2:3], v[2:3], v[158:159]
	v_pk_mul_f32 v[0:1], v[0:1], v[156:157]
	v_pk_mul_f32 v[60:61], v[60:61], v[144:145]
	v_pk_mul_f32 v[56:57], v[56:57], v[148:149]
	v_pk_mul_f32 v[52:53], v[52:53], v[152:153]
	v_pk_mul_f32 v[62:63], v[62:63], v[146:147]
	v_pk_mul_f32 v[58:59], v[58:59], v[150:151]
	v_pk_mul_f32 v[54:55], v[54:55], v[154:155]
	v_pk_mul_f32 v[50:51], v[50:51], v[158:159]
	v_pk_mul_f32 v[48:49], v[48:49], v[156:157]
	v_pk_mul_f32 v[44:45], v[44:45], v[144:145]
	v_pk_mul_f32 v[40:41], v[40:41], v[148:149]
	v_pk_mul_f32 v[36:37], v[36:37], v[152:153]
	v_pk_mul_f32 v[46:47], v[46:47], v[146:147]
	v_pk_mul_f32 v[42:43], v[42:43], v[150:151]
	v_pk_mul_f32 v[38:39], v[38:39], v[154:155]
	v_pk_mul_f32 v[34:35], v[34:35], v[158:159]
	v_pk_mul_f32 v[32:33], v[32:33], v[156:157]
	v_pk_mul_f32 v[28:29], v[28:29], v[144:145]
	v_pk_mul_f32 v[24:25], v[24:25], v[148:149]
	v_pk_mul_f32 v[20:21], v[20:21], v[152:153]
	v_pk_mul_f32 v[30:31], v[30:31], v[146:147]
	v_pk_mul_f32 v[26:27], v[26:27], v[150:151]
	v_pk_mul_f32 v[22:23], v[22:23], v[154:155]
	v_pk_mul_f32 v[18:19], v[18:19], v[158:159]
	v_pk_mul_f32 v[16:17], v[16:17], v[156:157]
.Lattn_slow_b_end:
	v_mov_b32_e32 v164, v161
	s_branch .LBB0_585
.Lattn_skip_loads:
	s_waitcnt vmcnt(0)
	s_branch .LBB0_581
; #define SBAR() __builtin_amdgcn_sched_barrier(0)
; __device__ __forceinline__ void finishSM(f32x16& p0, f32x16& p1, float alpha, float& l_reg, bf16x8& pa0, bf16x8& pa1, bf16x8& pa2, bf16x8& pa3) {
;     ...
;   float ps = 0; for (int r = 0; r < 16; ++r) ps += p0[r]; for (int r = 0; r < 16; ++r) ps += p1[r];
;   { auto rr = __builtin_amdgcn_permlane32_swap(__float_as_uint(ps), __float_as_uint(ps), false, false);
;     ps = __uint_as_float(rr[0]) + __uint_as_float(rr[1]); }
;   l_reg = l_reg * alpha + ps;
; template <typename TQ>
; __device__ __forceinline__ void attn_dense_body(const TQ* __restrict__ Qb, const bf16* __restrict__ Kh, const bf16* __restrict__ Vh,
;                                                 unsigned short* __restrict__ Ob, int seq, char* lds, const int wave_s) {
;     ...
;   SBAR(); qkt(pB0, pB1, (bf16*)((char*)K_lds + SHM_K), qr, r32, hi);
;   finishSM(pA0, pA1, alA, l_reg, pa0, pa1, pa2, pa3); SBAR();
;   pv_d0(o, vb0, pa0, pa1, pa2, pa3); partialSM(pB0, pB1, m_reg, mnB, alB);
.LBB0_587:
	v_mov_b32_e32 v204, v182
	s_nop 1
	v_permlane32_swap_b32_e32 v182, v204
	v_add_f32_e32 v182, v182, v204
	ds_read_b128 v[64:67], v189 offset:49152
	ds_read_b128 v[68:71], v189 offset:57344
	s_waitcnt lgkmcnt(1)
	v_mfma_f32_32x32x16_bf16 v[80:95], v[64:67], v[112:115], 0
	s_waitcnt lgkmcnt(0)
	v_mfma_f32_32x32x16_bf16 v[64:79], v[68:71], v[112:115], 0
	ds_read_b128 v[112:115], v199 offset:49152
	ds_read_b128 v[128:131], v199 offset:57344
	s_waitcnt lgkmcnt(1)
	v_mfma_f32_32x32x16_bf16 v[80:95], v[112:115], v[108:111], v[80:95]
	s_waitcnt lgkmcnt(0)
	v_mfma_f32_32x32x16_bf16 v[64:79], v[128:131], v[108:111], v[64:79]
	ds_read_b128 v[108:111], v192 offset:49152
	ds_read_b128 v[112:115], v192 offset:57344
	s_waitcnt lgkmcnt(1)
	v_mfma_f32_32x32x16_bf16 v[80:95], v[108:111], v[120:123], v[80:95]
	s_waitcnt lgkmcnt(0)
	v_mfma_f32_32x32x16_bf16 v[64:79], v[112:115], v[120:123], v[64:79]
	ds_read_b128 v[108:111], v191 offset:49152
	ds_read_b128 v[112:115], v191 offset:57344
	v_exp_f32_e32 v120, v144
	v_exp_f32_e32 v121, v145
	s_waitcnt lgkmcnt(1)
	v_mfma_f32_32x32x16_bf16 v[80:95], v[108:111], v[124:127], v[80:95]
	s_waitcnt lgkmcnt(0)
	v_mfma_f32_32x32x16_bf16 v[64:79], v[112:115], v[124:127], v[64:79]
	ds_read_b128 v[108:111], v189 offset:49280
	ds_read_b128 v[112:115], v189 offset:57472
	s_waitcnt lgkmcnt(1)
	v_mfma_f32_32x32x16_bf16 v[80:95], v[108:111], v[116:119], v[80:95]
	s_waitcnt lgkmcnt(0)
	v_mfma_f32_32x32x16_bf16 v[64:79], v[112:115], v[116:119], v[64:79]
	ds_read_b128 v[108:111], v199 offset:49280
	ds_read_b128 v[112:115], v199 offset:57472
	v_exp_f32_e32 v116, v154
	v_exp_f32_e32 v117, v155
	v_exp_f32_e32 v118, v150
	v_exp_f32_e32 v119, v151
	s_waitcnt lgkmcnt(1)
	v_mfma_f32_32x32x16_bf16 v[80:95], v[108:111], v[104:107], v[80:95]
	s_waitcnt lgkmcnt(0)
	v_mfma_f32_32x32x16_bf16 v[64:79], v[112:115], v[104:107], v[64:79]
	ds_read_b128 v[104:107], v192 offset:49280
	ds_read_b128 v[108:111], v192 offset:57472
	v_exp_f32_e32 v112, v148
	v_exp_f32_e32 v113, v149
	v_exp_f32_e32 v114, v146
	v_exp_f32_e32 v115, v147
	s_waitcnt lgkmcnt(1)
	v_mfma_f32_32x32x16_bf16 v[80:95], v[104:107], v[100:103], v[80:95]
	s_waitcnt lgkmcnt(0)
	v_mfma_f32_32x32x16_bf16 v[64:79], v[108:111], v[100:103], v[64:79]
	ds_read_b128 v[100:103], v191 offset:49280
	ds_read_b128 v[104:107], v191 offset:57472
	v_exp_f32_e32 v108, v156
	v_exp_f32_e32 v109, v157
	v_exp_f32_e32 v110, v152
	v_exp_f32_e32 v111, v153
	s_waitcnt lgkmcnt(1)
	v_mfma_f32_32x32x16_bf16 v[80:95], v[100:103], v[96:99], v[80:95]
	s_waitcnt lgkmcnt(0)
	v_mfma_f32_32x32x16_bf16 v[64:79], v[104:107], v[96:99], v[64:79]
	v_add_f32_e32 v96, 0, v161
	v_add_f32_e32 v96, v175, v96
	v_add_f32_e32 v96, v162, v96
	v_add_f32_e32 v96, v206, v96
	v_add_f32_e32 v96, v174, v96
	v_add_f32_e32 v96, v209, v96
	v_add_f32_e32 v96, v163, v96
	v_add_f32_e32 v96, v173, v96
	v_add_f32_e32 v96, v169, v96
	v_add_f32_e32 v96, v171, v96
	v_add_f32_e32 v96, v170, v96
	v_add_f32_e32 v96, v172, v96
	v_exp_f32_e32 v106, v158
	v_add_f32_e32 v96, v165, v96
	v_exp_f32_e32 v107, v159
	v_add_f32_e32 v96, v167, v96
	v_add_f32_e32 v96, v166, v96
	v_add_f32_e32 v96, v168, v96
	v_add_f32_e32 v96, v106, v96
	v_add_f32_e32 v96, v107, v96
	v_add_f32_e32 v96, v108, v96
	v_add_f32_e32 v96, v109, v96
	v_add_f32_e32 v96, v110, v96
	v_add_f32_e32 v96, v111, v96
	v_add_f32_e32 v96, v112, v96
	v_add_f32_e32 v96, v113, v96
	v_add_f32_e32 v96, v114, v96
	v_add_f32_e32 v96, v115, v96
	v_add_f32_e32 v96, v116, v96
	v_add_f32_e32 v96, v117, v96
	v_add_f32_e32 v96, v118, v96
	v_add_f32_e32 v96, v119, v96
	v_add_f32_e32 v96, v120, v96
	v_add_f32_e32 v96, v121, v96
	v_mov_b32_e32 v97, v96
	v_cvt_pk_bf16_f32 v98, v161, v175
	v_cvt_pk_bf16_f32 v99, v162, v206
	v_cvt_pk_bf16_f32 v100, v174, v209
	v_cvt_pk_bf16_f32 v101, v163, v173
	s_nop 1
	v_permlane32_swap_b32_e32 v96, v97
	v_cvt_pk_bf16_f32 v102, v169, v171
	v_cvt_pk_bf16_f32 v103, v170, v172
	v_cvt_pk_bf16_f32 v104, v165, v167
	v_cvt_pk_bf16_f32 v105, v166, v168
	v_cvt_pk_bf16_f32 v106, v106, v107
	v_cvt_pk_bf16_f32 v107, v108, v109
	v_cvt_pk_bf16_f32 v108, v110, v111
	v_cvt_pk_bf16_f32 v109, v112, v113
	v_cvt_pk_bf16_f32 v110, v114, v115
	v_cvt_pk_bf16_f32 v111, v116, v117
	v_cvt_pk_bf16_f32 v112, v118, v119
	v_cvt_pk_bf16_f32 v113, v120, v121
	s_nop 0
	ds_read_b64_tr_b16 v[114:115], v184 offset:0
	ds_read_b64_tr_b16 v[116:117], v184 offset:0x800
	ds_read_b64_tr_b16 v[118:119], v184 offset:0x1000
	ds_read_b64_tr_b16 v[120:121], v184 offset:0x1800
	ds_read_b64_tr_b16 v[122:123], v184 offset:0x2000
	ds_read_b64_tr_b16 v[124:125], v184 offset:0x2800
	ds_read_b64_tr_b16 v[126:127], v184 offset:0x3000
	ds_read_b64_tr_b16 v[128:129], v184 offset:0x3800
	s_waitcnt lgkmcnt(0)
; #define SBAR() __builtin_amdgcn_sched_barrier(0)
; #define RESC(a) do { if (__any((a) < 1.f)) { if (hi == 0) al_l[r32] = (a); asm volatile("s_waitcnt lgkmcnt(0)" ::: "memory"); \
;     for (int d = 0; d < 4; ++d) for (int r = 0; r < 16; ++r) o[d][r] *= al_l[crow(r, hi)]; } } while (0)
; __device__ __forceinline__ void partialSM(f32x16& p0, f32x16& p1, float& m_reg, float& mn, float& alpha) {
;     ...
;   float pmax = p0[0]; for (int r = 1; r < 16; ++r) pmax = fmaxf(pmax, p0[r]); for (int r = 0; r < 16; ++r) pmax = fmaxf(pmax, p1[r]);
;   { auto rr = __builtin_amdgcn_permlane32_swap(__float_as_uint(pmax), __float_as_uint(pmax), false, false);
;     pmax = fmaxf(__uint_as_float(rr[0]), __uint_as_float(rr[1])); }
;   if (__builtin_expect(__all(pmax - m_reg <= THR / SCALE), 1)) { mn = m_reg; alpha = 1.f; }
;   else { mn = fmaxf(m_reg, pmax); alpha = __builtin_amdgcn_exp2f((m_reg - mn) * C); m_reg = mn; }
; template <typename TQ>
; __device__ __forceinline__ void attn_dense_body(const TQ* __restrict__ Qb, const bf16* __restrict__ Kh, const bf16* __restrict__ Vh,
;                                                 unsigned short* __restrict__ Ob, int seq, char* lds, const int wave_s) {
;     ...
;   finishSM(pA0, pA1, alA, l_reg, pa0, pa1, pa2, pa3); SBAR();
;   pv_d0(o, vb0, pa0, pa1, pa2, pa3); partialSM(pB0, pB1, m_reg, mnB, alB);
;   __syncthreads(); RESC(alB);
	s_nop 0
	v_mfma_f32_32x32x16_bf16 v[0:15], v[98:101], v[114:117], v[0:15]
	ds_read_b64_tr_b16 v[114:115], v184 offset:0x200
	ds_read_b64_tr_b16 v[116:117], v184 offset:0xa00
	v_mfma_f32_32x32x16_bf16 v[0:15], v[102:105], v[118:121], v[0:15]
	ds_read_b64_tr_b16 v[118:119], v184 offset:0x1200
	ds_read_b64_tr_b16 v[120:121], v184 offset:0x1a00
	v_mfma_f32_32x32x16_bf16 v[0:15], v[106:109], v[122:125], v[0:15]
	ds_read_b64_tr_b16 v[122:123], v184 offset:0x2200
	ds_read_b64_tr_b16 v[124:125], v184 offset:0x2a00
	v_mfma_f32_32x32x16_bf16 v[0:15], v[110:113], v[126:129], v[0:15]
	ds_read_b64_tr_b16 v[126:127], v184 offset:0x3200
	ds_read_b64_tr_b16 v[128:129], v184 offset:0x3a00
	s_waitcnt lgkmcnt(0)
	v_mfma_f32_32x32x16_bf16 v[48:63], v[98:101], v[114:117], v[48:63]
	ds_read_b64_tr_b16 v[114:115], v184 offset:0x400
	ds_read_b64_tr_b16 v[116:117], v184 offset:0xc00
	v_mfma_f32_32x32x16_bf16 v[48:63], v[102:105], v[118:121], v[48:63]
	ds_read_b64_tr_b16 v[118:119], v184 offset:0x1400
	ds_read_b64_tr_b16 v[120:121], v184 offset:0x1c00
	v_mfma_f32_32x32x16_bf16 v[48:63], v[106:109], v[122:125], v[48:63]
	ds_read_b64_tr_b16 v[122:123], v184 offset:0x2400
	ds_read_b64_tr_b16 v[124:125], v184 offset:0x2c00
	v_mfma_f32_32x32x16_bf16 v[48:63], v[110:113], v[126:129], v[48:63]
	ds_read_b64_tr_b16 v[126:127], v184 offset:0x3400
	ds_read_b64_tr_b16 v[128:129], v184 offset:0x3c00
	s_waitcnt lgkmcnt(0)
	v_mfma_f32_32x32x16_bf16 v[32:47], v[98:101], v[114:117], v[32:47]
	ds_read_b64_tr_b16 v[114:115], v184 offset:0x600
	ds_read_b64_tr_b16 v[116:117], v184 offset:0xe00
	v_mfma_f32_32x32x16_bf16 v[32:47], v[102:105], v[118:121], v[32:47]
	ds_read_b64_tr_b16 v[118:119], v184 offset:0x1600
	ds_read_b64_tr_b16 v[120:121], v184 offset:0x1e00
	v_mfma_f32_32x32x16_bf16 v[32:47], v[106:109], v[122:125], v[32:47]
	ds_read_b64_tr_b16 v[122:123], v184 offset:0x2600
	ds_read_b64_tr_b16 v[124:125], v184 offset:0x2e00
	v_mfma_f32_32x32x16_bf16 v[32:47], v[110:113], v[126:129], v[32:47]
	ds_read_b64_tr_b16 v[126:127], v184 offset:0x3600
	ds_read_b64_tr_b16 v[128:129], v184 offset:0x3e00
	s_waitcnt lgkmcnt(0)
	v_mfma_f32_32x32x16_bf16 v[16:31], v[98:101], v[114:117], v[16:31]
	v_max_f32_e32 v98, v81, v81
	v_max_f32_e32 v99, v80, v80
	v_max_f32_e32 v98, v99, v98
	v_max3_f32 v98, v98, v82, v83
	v_max3_f32 v98, v98, v84, v85
	v_max3_f32 v98, v98, v86, v87
	v_max3_f32 v98, v98, v88, v89
	v_max3_f32 v98, v98, v90, v91
	v_max3_f32 v98, v98, v92, v93
	v_mfma_f32_32x32x16_bf16 v[16:31], v[102:105], v[118:121], v[16:31]
	v_max3_f32 v98, v98, v94, v95
	v_max3_f32 v98, v98, v64, v65
	v_max3_f32 v98, v98, v66, v67
	v_max3_f32 v98, v98, v68, v69
	v_max3_f32 v98, v98, v70, v71
	v_max3_f32 v98, v98, v72, v73
	v_max3_f32 v98, v98, v74, v75
	v_max3_f32 v98, v98, v76, v77
	v_mfma_f32_32x32x16_bf16 v[16:31], v[106:109], v[122:125], v[16:31]
	v_max3_f32 v98, v98, v78, v79
	v_mov_b32_e32 v99, v98
	s_nop 1
	v_permlane32_swap_b32_e32 v98, v99
	v_max_f32_e32 v99, v99, v99
	v_max_f32_e32 v98, v98, v98
	v_max_f32_e32 v98, v98, v99
	v_sub_f32_e32 v99, v98, v164
	v_cmp_ge_f32_e32 vcc, s9, v99
	v_max_f32_e32 v99, v164, v164
	v_max_f32_e32 v99, v99, v98
	v_mfma_f32_32x32x16_bf16 v[16:31], v[110:113], v[126:129], v[16:31]
	v_sub_f32_e32 v98, v164, v99
	v_mul_f32_e32 v98, 0x3e0293ee, v98
	v_exp_f32_e32 v98, v98
	s_cmp_eq_u64 vcc, exec
	s_cselect_b64 s[40:41], -1, 0
	v_cndmask_b32_e64 v98, v98, 1.0, s[40:41]
	v_cmp_gt_f32_e32 vcc, 1.0, v98
	s_barrier
	s_cbranch_vccz .LBB0_591
	s_and_saveexec_b64 s[44:45], s[38:39]
	ds_write_b32 v181, v98 offset:128
	s_or_b64 exec, exec, s[44:45]
	s_waitcnt lgkmcnt(0)
	v_add_u32_e32 v112, s1, v180
	ds_read_b128 v[100:103], v112 offset:224
	ds_read_b128 v[104:107], v112 offset:192
	ds_read_b128 v[108:111], v112 offset:160
	ds_read_b128 v[112:115], v112 offset:128
	s_waitcnt lgkmcnt(3)
	v_pk_mul_f32 v[12:13], v[12:13], v[100:101]
	s_waitcnt lgkmcnt(2)
	v_pk_mul_f32 v[8:9], v[8:9], v[104:105]
	s_waitcnt lgkmcnt(1)
	v_pk_mul_f32 v[4:5], v[4:5], v[108:109]
	v_pk_mul_f32 v[14:15], v[14:15], v[102:103]
	v_pk_mul_f32 v[10:11], v[10:11], v[106:107]
	v_pk_mul_f32 v[6:7], v[6:7], v[110:111]
	s_waitcnt lgkmcnt(0)
	v_pk_mul_f32 v[2:3], v[2:3], v[114:115]
	v_pk_mul_f32 v[0:1], v[0:1], v[112:113]
	v_pk_mul_f32 v[60:61], v[60:61], v[100:101]
	v_pk_mul_f32 v[56:57], v[56:57], v[104:105]
	v_pk_mul_f32 v[52:53], v[52:53], v[108:109]
	v_pk_mul_f32 v[62:63], v[62:63], v[102:103]
	v_pk_mul_f32 v[58:59], v[58:59], v[106:107]
	v_pk_mul_f32 v[54:55], v[54:55], v[110:111]
	v_pk_mul_f32 v[50:51], v[50:51], v[114:115]
	v_pk_mul_f32 v[48:49], v[48:49], v[112:113]
	v_pk_mul_f32 v[44:45], v[44:45], v[100:101]
	v_pk_mul_f32 v[40:41], v[40:41], v[104:105]
	v_pk_mul_f32 v[36:37], v[36:37], v[108:109]
	v_pk_mul_f32 v[46:47], v[46:47], v[102:103]
	v_pk_mul_f32 v[42:43], v[42:43], v[106:107]
	v_pk_mul_f32 v[38:39], v[38:39], v[110:111]
	v_pk_mul_f32 v[34:35], v[34:35], v[114:115]
	v_pk_mul_f32 v[32:33], v[32:33], v[112:113]
	v_pk_mul_f32 v[28:29], v[28:29], v[100:101]
	v_pk_mul_f32 v[24:25], v[24:25], v[104:105]
	v_pk_mul_f32 v[20:21], v[20:21], v[108:109]
	v_pk_mul_f32 v[30:31], v[30:31], v[102:103]
	v_pk_mul_f32 v[26:27], v[26:27], v[106:107]
	v_pk_mul_f32 v[22:23], v[22:23], v[110:111]
	v_pk_mul_f32 v[18:19], v[18:19], v[114:115]
	v_pk_mul_f32 v[16:17], v[16:17], v[112:113]
